# diff-attention tile loops: K-fragment LDS reads batched ahead of the QK MFMAs with counted lgkmcnt waits, next-tile LDS-DMA issued under the read latency; V-fragment reads ring-buffered one key group
# speedup vs baseline: 1.0064x; 1.0064x over previous
; #define LAS __attribute__((address_space(3)))
; __device__ __forceinline__ float ex2(float v) { return __builtin_amdgcn_exp2f(v); }
; #define MFMA32(a, b, c) __builtin_amdgcn_mfma_f32_32x32x16_bf16((a), (b), (c), 0, 0, 0)
; #define SCHEDB() __builtin_amdgcn_sched_barrier(0)
; __device__ __forceinline__ void diff_unit(const Params& p, LAS unsigned char* lds, int b, int h, int qb, float lam) {
;     ...
; #pragma unroll
;                 for (int r = 0; r < 16; ++r) s0[r] = ex2(s0[r]);
; #pragma unroll
;                 for (int g = 0; g < 4; ++g) {
;                     const int co = ((4 * (g >> 1) + (g & 1)) ^ xv) << 4;
;                     bf16x8 vf[4];
; #pragma unroll
;                     for (int db = 0; db < 4; ++db) vf[db] = *(const LAS bf16x8*)(vb + db * 4096 + co);
;                     const bf16x8 pf = pack8((g >> 1) ? s1 : s0, 8 * (g & 1));
; #pragma unroll
;                     for (int db = 0; db < 4; ++db) O[db] = MFMA32(pf, vf[db], O[db]);
;                     L = MFMA32(pf, ones, L);
;                     if (g < 2) {
; #pragma unroll
;                         for (int r = 0; r < 8; ++r) s1[8 * g + r] = ex2(s1[8 * g + r]);
;                     }
;                     SCHEDB();
;                 }
.LBB0_266:
	v_exp_f32_e32 v0, v112
	v_exp_f32_e32 v112, v113
	v_exp_f32_e32 v113, v114
	v_exp_f32_e32 v114, v115
	v_exp_f32_e32 v115, v116
	v_exp_f32_e32 v116, v117
	v_exp_f32_e32 v117, v118
	v_exp_f32_e32 v118, v119
	v_add_u32_e32 v244, v197, v198
	ds_read_b128 v[240:243], v244 offset:49152
	ds_read_b128 v[236:239], v244 offset:53248
	ds_read_b128 v[232:235], v244 offset:57344
	ds_read_b128 v[228:231], v244 offset:61440
	v_add_u32_e32 v244, v197, v199
	ds_read_b128 v[216:219], v244 offset:49152
	ds_read_b128 v[208:211], v244 offset:53248
	v_cvt_pk_bf16_f32 v112, v0, v112
	v_cvt_pk_bf16_f32 v113, v113, v114
	v_cvt_pk_bf16_f32 v114, v115, v116
	v_cvt_pk_bf16_f32 v115, v117, v118
	s_waitcnt lgkmcnt(5)
	s_nop 0
	v_mfma_f32_32x32x16_bf16 v[16:31], v[112:115], v[240:243], v[16:31]
	ds_read_b128 v[240:243], v244 offset:57344
	s_mov_b32 s10, s8
	s_mov_b32 s11, s8
	s_mov_b32 s9, s8
	v_exp_f32_e32 v0, v120
	v_exp_f32_e32 v120, v121
	v_exp_f32_e32 v121, v122
	s_waitcnt lgkmcnt(5)
	v_mfma_f32_32x32x16_bf16 v[32:47], v[112:115], v[236:239], v[32:47]
	ds_read_b128 v[236:239], v244 offset:61440
	v_exp_f32_e32 v122, v123
	v_exp_f32_e32 v123, v124
	v_exp_f32_e32 v124, v125
	v_exp_f32_e32 v125, v126
	v_exp_f32_e32 v126, v127
	v_exp_f32_e32 v127, v96
	s_waitcnt lgkmcnt(5)
	v_mfma_f32_32x32x16_bf16 v[48:63], v[112:115], v[232:235], v[48:63]
	v_add_u32_e32 v244, v197, v200
	ds_read_b128 v[232:235], v244 offset:49152
	v_mov_b64_e32 v[118:119], s[10:11]
	v_mov_b64_e32 v[116:117], s[8:9]
	v_exp_f32_e32 v132, v101
	v_exp_f32_e32 v133, v102
	v_exp_f32_e32 v134, v103
	s_waitcnt lgkmcnt(5)
	v_mfma_f32_32x32x16_bf16 v[64:79], v[112:115], v[228:231], v[64:79]
	ds_read_b128 v[228:231], v244 offset:53248
	v_exp_f32_e32 v128, v97
	v_exp_f32_e32 v129, v98
	v_exp_f32_e32 v130, v99
	v_exp_f32_e32 v131, v100
	v_mfma_f32_32x32x16_bf16 v[80:95], v[112:115], v[116:119], v[80:95]
	v_cvt_pk_bf16_f32 v96, v0, v120
	v_cvt_pk_bf16_f32 v97, v121, v122
	v_cvt_pk_bf16_f32 v98, v123, v124
	v_cvt_pk_bf16_f32 v99, v125, v126
	s_waitcnt lgkmcnt(5)
	s_nop 0
	v_mfma_f32_32x32x16_bf16 v[16:31], v[96:99], v[216:219], v[16:31]
	ds_read_b128 v[216:219], v244 offset:57344
	v_exp_f32_e32 v0, v104
	v_exp_f32_e32 v108, v108
	v_exp_f32_e32 v109, v109
	v_exp_f32_e32 v110, v110
	v_exp_f32_e32 v111, v111
	s_waitcnt lgkmcnt(5)
	v_mfma_f32_32x32x16_bf16 v[32:47], v[96:99], v[208:211], v[32:47]
	ds_read_b128 v[208:211], v244 offset:61440
	s_waitcnt lgkmcnt(5)
	v_mfma_f32_32x32x16_bf16 v[48:63], v[96:99], v[240:243], v[48:63]
	v_add_u32_e32 v244, v197, v201
	ds_read_b128 v[240:243], v244 offset:49152
	s_waitcnt lgkmcnt(5)
	v_mfma_f32_32x32x16_bf16 v[64:79], v[96:99], v[236:239], v[64:79]
	ds_read_b128 v[236:239], v244 offset:53248
	v_exp_f32_e32 v112, v105
	v_exp_f32_e32 v113, v106
	v_exp_f32_e32 v114, v107
	v_mfma_f32_32x32x16_bf16 v[80:95], v[96:99], v[116:119], v[80:95]
	v_cvt_pk_bf16_f32 v96, v127, v128
	v_cvt_pk_bf16_f32 v97, v129, v130
	v_cvt_pk_bf16_f32 v98, v131, v132
	v_cvt_pk_bf16_f32 v99, v133, v134
	s_waitcnt lgkmcnt(5)
	s_nop 0
	v_mfma_f32_32x32x16_bf16 v[16:31], v[96:99], v[232:235], v[16:31]
	ds_read_b128 v[232:235], v244 offset:57344
	s_waitcnt lgkmcnt(5)
	v_mfma_f32_32x32x16_bf16 v[32:47], v[96:99], v[228:231], v[32:47]
	ds_read_b128 v[228:231], v244 offset:61440
	s_waitcnt lgkmcnt(5)
	v_mfma_f32_32x32x16_bf16 v[48:63], v[96:99], v[216:219], v[48:63]
	s_waitcnt lgkmcnt(4)
	v_mfma_f32_32x32x16_bf16 v[64:79], v[96:99], v[208:211], v[64:79]
	v_mfma_f32_32x32x16_bf16 v[80:95], v[96:99], v[116:119], v[80:95]
	v_cvt_pk_bf16_f32 v96, v0, v112
	v_cvt_pk_bf16_f32 v97, v113, v114
	v_cvt_pk_bf16_f32 v98, v108, v109
	v_cvt_pk_bf16_f32 v99, v110, v111
	s_waitcnt lgkmcnt(3)
	s_nop 0
	v_mfma_f32_32x32x16_bf16 v[16:31], v[96:99], v[240:243], v[16:31]
	s_waitcnt lgkmcnt(2)
	v_mfma_f32_32x32x16_bf16 v[32:47], v[96:99], v[236:239], v[32:47]
	s_waitcnt lgkmcnt(1)
	v_mfma_f32_32x32x16_bf16 v[48:63], v[96:99], v[232:235], v[48:63]
	s_waitcnt lgkmcnt(0)
	v_mfma_f32_32x32x16_bf16 v[64:79], v[96:99], v[228:231], v[64:79]
	v_mfma_f32_32x32x16_bf16 v[80:95], v[96:99], v[116:119], v[80:95]

; #define LAS __attribute__((address_space(3)))
; __device__ __forceinline__ float ex2(float v) { return __builtin_amdgcn_exp2f(v); }
; #define MFMA32(a, b, c) __builtin_amdgcn_mfma_f32_32x32x16_bf16((a), (b), (c), 0, 0, 0)
; #define SCHEDB() __builtin_amdgcn_sched_barrier(0)
; __device__ __forceinline__ void diff_unit(const Params& p, LAS unsigned char* lds, int b, int h, int qb, float lam) {
;     ...
; #pragma unroll
;                 for (int r = 0; r < 16; ++r) s0[r] = ex2(s0[r]);
; #pragma unroll
;                 for (int g = 0; g < 4; ++g) {
;                     const int co = ((4 * (g >> 1) + (g & 1)) ^ xv) << 4;
;                     bf16x8 vf[4];
; #pragma unroll
;                     for (int db = 0; db < 4; ++db) vf[db] = *(const LAS bf16x8*)(vb + db * 4096 + co);
;                     const bf16x8 pf = pack8((g >> 1) ? s1 : s0, 8 * (g & 1));
; #pragma unroll
;                     for (int db = 0; db < 4; ++db) O[db] = MFMA32(pf, vf[db], O[db]);
;                     L = MFMA32(pf, ones, L);
;                     if (g < 2) {
; #pragma unroll
;                         for (int r = 0; r < 8; ++r) s1[8 * g + r] = ex2(s1[8 * g + r]);
;                     }
;                     SCHEDB();
;                 }
.LBB0_283:
	v_add_u32_e32 v244, v4, v198
	ds_read_b128 v[240:243], v244 offset:32768
	ds_read_b128 v[236:239], v244 offset:36864
	ds_read_b128 v[232:235], v244 offset:40960
	ds_read_b128 v[228:231], v244 offset:45056
	v_add_u32_e32 v244, v4, v199
	ds_read_b128 v[216:219], v244 offset:32768
	v_exp_f32_e32 v5, v128
	v_exp_f32_e32 v14, v129
	v_exp_f32_e32 v15, v130
	v_exp_f32_e32 v183, v131
	v_exp_f32_e32 v184, v132
	v_exp_f32_e32 v185, v133
	v_exp_f32_e32 v186, v134
	v_exp_f32_e32 v187, v135
	v_exp_f32_e32 v188, v136
	v_exp_f32_e32 v189, v137
	v_exp_f32_e32 v209, v138
	v_exp_f32_e32 v210, v139
	v_cvt_pk_bf16_f32 v136, v5, v14
	v_cvt_pk_bf16_f32 v137, v15, v183
	v_cvt_pk_bf16_f32 v138, v184, v185
	v_cvt_pk_bf16_f32 v139, v186, v187
	s_mov_b32 s9, s8
	s_waitcnt lgkmcnt(4)
	v_mfma_f32_32x32x16_bf16 v[16:31], v[136:139], v[240:243], v[16:31]
	ds_read_b128 v[240:243], v244 offset:36864
	s_mov_b32 s10, s8
	s_mov_b32 s11, s8
	v_mov_b64_e32 v[6:7], s[8:9]
	v_mov_b64_e32 v[8:9], s[10:11]
	v_exp_f32_e32 v140, v140
	v_exp_f32_e32 v141, v141
	v_exp_f32_e32 v142, v142
	s_waitcnt lgkmcnt(4)
	v_mfma_f32_32x32x16_bf16 v[32:47], v[136:139], v[236:239], v[32:47]
	ds_read_b128 v[236:239], v244 offset:40960
	v_exp_f32_e32 v143, v143
	v_exp_f32_e32 v5, v112
	v_exp_f32_e32 v14, v113
	v_exp_f32_e32 v15, v114
	v_exp_f32_e32 v116, v116
	v_exp_f32_e32 v117, v117
	v_exp_f32_e32 v118, v118
	s_waitcnt lgkmcnt(4)
	v_mfma_f32_32x32x16_bf16 v[48:63], v[136:139], v[232:235], v[48:63]
	ds_read_b128 v[232:235], v244 offset:45056
	v_exp_f32_e32 v128, v115
	v_exp_f32_e32 v119, v119
	s_waitcnt lgkmcnt(4)
	v_mfma_f32_32x32x16_bf16 v[64:79], v[136:139], v[228:231], v[64:79]
	v_add_u32_e32 v244, v4, v200
	ds_read_b128 v[228:231], v244 offset:32768
	v_mfma_f32_32x32x16_bf16 v[80:95], v[136:139], v[6:9], v[80:95]
	v_cvt_pk_bf16_f32 v10, v188, v189
	v_cvt_pk_bf16_f32 v11, v209, v210
	v_cvt_pk_bf16_f32 v12, v140, v141
	v_cvt_pk_bf16_f32 v13, v142, v143
	v_exp_f32_e32 v120, v120
	s_waitcnt lgkmcnt(4)
	v_mfma_f32_32x32x16_bf16 v[16:31], v[10:13], v[216:219], v[16:31]
	ds_read_b128 v[216:219], v244 offset:36864
	v_exp_f32_e32 v121, v121
	v_exp_f32_e32 v122, v122
	v_exp_f32_e32 v123, v123
	v_exp_f32_e32 v124, v124
	v_exp_f32_e32 v125, v125
	v_exp_f32_e32 v126, v126
	s_waitcnt lgkmcnt(4)
	v_mfma_f32_32x32x16_bf16 v[32:47], v[10:13], v[240:243], v[32:47]
	ds_read_b128 v[240:243], v244 offset:40960
	v_exp_f32_e32 v127, v127
	s_waitcnt lgkmcnt(4)
	v_mfma_f32_32x32x16_bf16 v[48:63], v[10:13], v[236:239], v[48:63]
	ds_read_b128 v[236:239], v244 offset:45056
	s_waitcnt lgkmcnt(4)
	v_mfma_f32_32x32x16_bf16 v[64:79], v[10:13], v[232:235], v[64:79]
	v_add_u32_e32 v244, v4, v201
	ds_read_b128 v[232:235], v244 offset:32768
	v_mfma_f32_32x32x16_bf16 v[80:95], v[10:13], v[6:9], v[80:95]
	v_cvt_pk_bf16_f32 v10, v5, v14
	v_cvt_pk_bf16_f32 v11, v15, v128
	v_cvt_pk_bf16_f32 v12, v116, v117
	v_cvt_pk_bf16_f32 v13, v118, v119
	s_waitcnt lgkmcnt(4)
	s_nop 0
	v_mfma_f32_32x32x16_bf16 v[16:31], v[10:13], v[228:231], v[16:31]
	ds_read_b128 v[228:231], v244 offset:36864
	s_waitcnt lgkmcnt(4)
	v_mfma_f32_32x32x16_bf16 v[32:47], v[10:13], v[216:219], v[32:47]
	ds_read_b128 v[216:219], v244 offset:40960
	s_waitcnt lgkmcnt(4)
	v_mfma_f32_32x32x16_bf16 v[48:63], v[10:13], v[240:243], v[48:63]
	ds_read_b128 v[240:243], v244 offset:45056
	s_waitcnt lgkmcnt(4)
	v_mfma_f32_32x32x16_bf16 v[64:79], v[10:13], v[236:239], v[64:79]
	v_mfma_f32_32x32x16_bf16 v[80:95], v[10:13], v[6:9], v[80:95]
	v_add_u32_e32 v4, v4, v201
	v_cvt_pk_bf16_f32 v10, v120, v121
	v_cvt_pk_bf16_f32 v11, v122, v123
	v_cvt_pk_bf16_f32 v12, v124, v125
	v_cvt_pk_bf16_f32 v13, v126, v127
	s_waitcnt lgkmcnt(3)
	s_nop 0
	v_mfma_f32_32x32x16_bf16 v[16:31], v[10:13], v[232:235], v[16:31]
	s_waitcnt lgkmcnt(2)
	v_mfma_f32_32x32x16_bf16 v[32:47], v[10:13], v[228:231], v[32:47]
	s_waitcnt lgkmcnt(1)
	v_mfma_f32_32x32x16_bf16 v[48:63], v[10:13], v[216:219], v[48:63]
	s_waitcnt lgkmcnt(0)
	v_mfma_f32_32x32x16_bf16 v[64:79], v[10:13], v[240:243], v[64:79]
	v_mfma_f32_32x32x16_bf16 v[80:95], v[10:13], v[6:9], v[80:95]

; #define LAS __attribute__((address_space(3)))
; #define MFMA32(a, b, c) __builtin_amdgcn_mfma_f32_32x32x16_bf16((a), (b), (c), 0, 0, 0)
; #define SCHEDB() __builtin_amdgcn_sched_barrier(0)
; __device__ __forceinline__ void diff_unit(const Params& p, LAS unsigned char* lds, int b, int h, int qb, float lam) {
;     ...
;         for (int jt = 0; jt < NT; ++jt) {
;             const int cur = jt & 1;
;             if (jt + 1 < NT) tile_dma<64>(Kg0 + (size_t)(jt + 1) * 4096, Vg0 + (size_t)(jt + 1) * 8192, lds + A_KOFF + (cur ^ 1) * A_KBUF, lds + A_VOFF + (cur ^ 1) * A_VBUF, wid, lane);
;             if (jt <= mylast) {
;                 const LAS unsigned char* kb = lds + A_KOFF + cur * A_KBUF + c * 128;
;                 const LAS unsigned char* vb = lds + A_VOFF + cur * A_VBUF + c * 128;
;                 f32x16 s0, s1;
;                 {
;                     bf16x8 a[2][2];
;                     { const int co = (0 ^ xk) << 4; a[0][0] = *(const LAS bf16x8*)(kb + co); a[0][1] = *(const LAS bf16x8*)(kb + 4096 + co); }
; #pragma unroll
;                     for (int ks = 0; ks < 4; ++ks) {
;                         if (ks + 1 < 4) { const int co = ((2 * (ks + 1)) ^ xk) << 4; a[(ks + 1) & 1][0] = *(const LAS bf16x8*)(kb + co); a[(ks + 1) & 1][1] = *(const LAS bf16x8*)(kb + 4096 + co); }
;                         if (ks == 0) { s0 = MFMA32(a[0][0], qf[0], negm); s1 = MFMA32(a[0][1], qf[0], negm); }
;                         else { s0 = MFMA32(a[ks & 1][0], qf[ks], s0); s1 = MFMA32(a[ks & 1][1], qf[ks], s1); }
;                         SCHEDB();
;                     }
;                 }
.LBB0_285:
	s_mov_b64 s[10:11], s[4:5]
	s_add_u32 s4, s10, 0x4000
	s_addc_u32 s5, s11, 0
	s_and_b32 s6, s4, 0x4000
	s_xor_b32 s9, s6, 0x4000
	s_add_i32 s22, s9, 0
	s_cmp_gt_i32 s1, s76
	s_cbranch_scc1 .Lqs0_dma_only
	v_add_u32_e32 v4, s6, v197
	v_add_u32_e32 v5, v4, v203
	ds_read_b128 v[6:9], v5
	ds_read_b128 v[10:13], v5 offset:4096
	v_add_u32_e32 v5, v4, v205
	ds_read_b128 v[228:231], v5
	ds_read_b128 v[184:187], v5 offset:4096
	v_add_u32_e32 v5, v4, v206
	ds_read_b128 v[232:235], v5
	ds_read_b128 v[236:239], v5 offset:4096
	v_add_u32_e32 v5, v4, v207
	ds_read_b128 v[240:243], v5
	ds_read_b128 v[216:219], v5 offset:4096
	s_add_i32 m0, s78, s9
	s_add_i32 s9, s22, s80
	global_load_lds_dwordx4 v[2:3], off
	v_lshl_add_u64 v[14:15], v[166:167], 0, s[10:11]
	s_add_i32 m0, s9, 0x8000
	s_add_i32 s9, s22, s79
	global_load_lds_dwordx4 v[14:15], off
	v_lshl_add_u64 v[14:15], v[168:169], 0, s[10:11]
	s_add_i32 m0, s9, 0x8000
	s_nop 0
	global_load_lds_dwordx4 v[14:15], off
	s_waitcnt lgkmcnt(7)
	v_mfma_f32_32x32x16_bf16 v[128:143], v[6:9], v[156:159], v[96:111]
	s_waitcnt lgkmcnt(6)
	v_mfma_f32_32x32x16_bf16 v[112:127], v[10:13], v[156:159], v[96:111]
	s_waitcnt lgkmcnt(5)
	v_mfma_f32_32x32x16_bf16 v[128:143], v[228:231], v[152:155], v[128:143]
	s_waitcnt lgkmcnt(4)
	v_mfma_f32_32x32x16_bf16 v[112:127], v[184:187], v[152:155], v[112:127]
	s_waitcnt lgkmcnt(3)
	v_mfma_f32_32x32x16_bf16 v[128:143], v[232:235], v[148:151], v[128:143]
	s_waitcnt lgkmcnt(2)
	v_mfma_f32_32x32x16_bf16 v[112:127], v[236:239], v[148:151], v[112:127]
	s_waitcnt lgkmcnt(1)
	v_mfma_f32_32x32x16_bf16 v[128:143], v[240:243], v[144:147], v[128:143]
	s_waitcnt lgkmcnt(0)
	v_mfma_f32_32x32x16_bf16 v[112:127], v[216:219], v[144:147], v[112:127]
	s_add_i32 s6, s3, 0xffffff81
	s_cmpk_gt_i32 s6, 0x5a
	s_cbranch_scc1 .LBB0_288
	v_add_u32_e32 v5, s3, v208
	s_add_i32 s6, 0, 0x10000
	v_min_i32_e32 v8, 0xc0, v5
	v_lshl_add_u32 v9, v8, 2, s6
	v_min_i32_e32 v8, 0xe0, v5
	v_lshl_add_u32 v10, v8, 2, s6
	v_min_i32_e32 v8, 0xc1, v5
	v_lshl_add_u32 v11, v8, 2, s6
	v_min_i32_e32 v8, 0xe1, v5
	v_min_i32_e32 v6, 0xbf, v5
	v_min_i32_e32 v7, 0xdf, v5
	v_lshl_add_u32 v12, v8, 2, s6
	v_min_i32_e32 v8, 0xc2, v5
	v_lshl_add_u32 v6, v6, 2, s6
	v_lshl_add_u32 v7, v7, 2, s6
	v_lshl_add_u32 v13, v8, 2, s6
	v_min_i32_e32 v8, 0xe2, v5
	v_lshl_add_u32 v14, v8, 2, s6
	ds_read_b32 v6, v6 offset:256
	ds_read_b32 v8, v7 offset:128
	ds_read_b32 v7, v9 offset:252
	ds_read_b32 v9, v10 offset:124
	ds_read_b32 v10, v11 offset:248
	ds_read_b32 v12, v12 offset:120
	ds_read_b32 v11, v13 offset:244
	ds_read_b32 v13, v14 offset:116
	v_min_i32_e32 v184, 0xe4, v5
	v_lshl_add_u32 v185, v184, 2, s6
	v_min_i32_e32 v184, 0xc5, v5
	v_lshl_add_u32 v186, v184, 2, s6
	v_min_i32_e32 v184, 0xe5, v5
	v_min_i32_e32 v14, 0xc3, v5
	v_min_i32_e32 v15, 0xe3, v5
	v_lshl_add_u32 v187, v184, 2, s6
	v_min_i32_e32 v184, 0xc6, v5
	v_lshl_add_u32 v14, v14, 2, s6
	v_lshl_add_u32 v15, v15, 2, s6
	v_min_i32_e32 v183, 0xc4, v5
	v_lshl_add_u32 v189, v184, 2, s6
	v_min_i32_e32 v184, 0xe6, v5
	v_lshl_add_u32 v183, v183, 2, s6
	v_lshl_add_u32 v209, v184, 2, s6
	ds_read_b32 v14, v14 offset:240
	ds_read_b32 v184, v15 offset:112
	ds_read_b32 v15, v183 offset:236
	ds_read_b32 v185, v185 offset:108
	ds_read_b32 v186, v186 offset:232
	ds_read_b32 v188, v187 offset:104
	ds_read_b32 v187, v189 offset:228
	ds_read_b32 v189, v209 offset:100
	v_min_i32_e32 v210, 0xc8, v5
	v_lshl_add_u32 v211, v210, 2, s6
	v_min_i32_e32 v210, 0xe8, v5
	v_lshl_add_u32 v213, v210, 2, s6
	v_min_i32_e32 v210, 0xc9, v5
	v_lshl_add_u32 v214, v210, 2, s6
	v_min_i32_e32 v210, 0xe9, v5
	v_min_i32_e32 v183, 0xc7, v5
	v_lshl_add_u32 v215, v210, 2, s6
	v_min_i32_e32 v210, 0xca, v5
	v_lshl_add_u32 v183, v183, 2, s6
	v_min_i32_e32 v209, 0xe7, v5
	v_lshl_add_u32 v217, v210, 2, s6
	v_min_i32_e32 v210, 0xea, v5
	v_lshl_add_u32 v209, v209, 2, s6
	v_lshl_add_u32 v218, v210, 2, s6
	ds_read_b32 v210, v183 offset:224
	ds_read_b32 v212, v209 offset:96
	ds_read_b32 v211, v211 offset:220
	ds_read_b32 v213, v213 offset:92
	ds_read_b32 v214, v214 offset:216
	ds_read_b32 v216, v215 offset:88
	ds_read_b32 v215, v217 offset:212
	ds_read_b32 v217, v218 offset:84
	v_min_i32_e32 v183, 0xcb, v5
	v_lshl_add_u32 v183, v183, 2, s6
	v_min_i32_e32 v209, 0xeb, v5
	v_min_i32_e32 v218, 0xcc, v5
	v_min_i32_e32 v219, 0xec, v5
	v_min_i32_e32 v220, 0xcd, v5
	v_min_i32_e32 v221, 0xed, v5
	v_min_i32_e32 v222, 0xce, v5
	v_min_i32_e32 v5, 0xee, v5
	v_lshl_add_u32 v209, v209, 2, s6
	v_lshl_add_u32 v218, v218, 2, s6
	v_lshl_add_u32 v219, v219, 2, s6
	v_lshl_add_u32 v220, v220, 2, s6
	v_lshl_add_u32 v221, v221, 2, s6
	v_lshl_add_u32 v222, v222, 2, s6
	s_waitcnt lgkmcnt(0)
	v_pk_add_f32 v[130:131], v[130:131], v[10:11]
	v_pk_add_f32 v[128:129], v[128:129], v[6:7]
	v_pk_add_f32 v[134:135], v[134:135], v[186:187]
	v_pk_add_f32 v[132:133], v[132:133], v[14:15]
	v_lshl_add_u32 v5, v5, 2, s6
	ds_read_b32 v6, v183 offset:208
	ds_read_b32 v10, v209 offset:80
	ds_read_b32 v14, v220 offset:200
	ds_read_b32 v15, v222 offset:196
	ds_read_b32 v7, v218 offset:204
	ds_read_b32 v187, v5 offset:68
	ds_read_b32 v186, v221 offset:72
	ds_read_b32 v11, v219 offset:76
	v_pk_add_f32 v[138:139], v[138:139], v[214:215]
	v_pk_add_f32 v[136:137], v[136:137], v[210:211]
	s_waitcnt lgkmcnt(0)
	v_pk_add_f32 v[142:143], v[142:143], v[14:15]
	v_pk_add_f32 v[140:141], v[140:141], v[6:7]
	v_pk_add_f32 v[114:115], v[114:115], v[12:13]
	v_pk_add_f32 v[112:113], v[112:113], v[8:9]
	v_pk_add_f32 v[118:119], v[118:119], v[188:189]
	v_pk_add_f32 v[116:117], v[116:117], v[184:185]
	v_pk_add_f32 v[122:123], v[122:123], v[216:217]
	v_pk_add_f32 v[120:121], v[120:121], v[212:213]
	v_pk_add_f32 v[126:127], v[126:127], v[186:187]
	v_pk_add_f32 v[124:125], v[124:125], v[10:11]

; __device__ __forceinline__ void diff_unit(const Params& p, LAS unsigned char* lds, int b, int h, int qb, float lam) {
;     ...
;             if (jt + 1 < NT) tile_dma<64>(Kg0 + (size_t)(jt + 1) * 4096, Vg0 + (size_t)(jt + 1) * 8192, lds + A_KOFF + (cur ^ 1) * A_KBUF, lds + A_VOFF + (cur ^ 1) * A_VBUF, wid, lane);
.Lqs0_dma_only:
	s_add_i32 m0, s78, s9
	s_add_i32 s9, s22, s80
	global_load_lds_dwordx4 v[2:3], off
	v_lshl_add_u64 v[4:5], v[166:167], 0, s[10:11]
	s_add_i32 m0, s9, 0x8000
	s_add_i32 s9, s22, s79
	global_load_lds_dwordx4 v[4:5], off
	v_lshl_add_u64 v[4:5], v[168:169], 0, s[10:11]
	s_add_i32 m0, s9, 0x8000
	s_nop 0
	global_load_lds_dwordx4 v[4:5], off
	s_branch .LBB0_284

; #define LAS __attribute__((address_space(3)))
; __device__ __forceinline__ float ex2(float v) { return __builtin_amdgcn_exp2f(v); }
; #define MFMA32(a, b, c) __builtin_amdgcn_mfma_f32_32x32x16_bf16((a), (b), (c), 0, 0, 0)
; #define SCHEDB() __builtin_amdgcn_sched_barrier(0)
; __device__ __forceinline__ void diff_unit(const Params& p, LAS unsigned char* lds, int b, int h, int qb, float lam) {
;     ...
; #pragma unroll
;                 for (int r = 0; r < 16; ++r) s0[r] = ex2(s0[r]);
; #pragma unroll
;                 for (int g = 0; g < 4; ++g) {
;                     const int co = ((4 * (g >> 1) + (g & 1)) ^ xv) << 4;
;                     bf16x8 vf[4];
; #pragma unroll
;                     for (int db = 0; db < 4; ++db) vf[db] = *(const LAS bf16x8*)(vb + db * 4096 + co);
;                     const bf16x8 pf = pack8((g >> 1) ? s1 : s0, 8 * (g & 1));
; #pragma unroll
;                     for (int db = 0; db < 4; ++db) O[db] = MFMA32(pf, vf[db], O[db]);
;                     L = MFMA32(pf, ones, L);
;                     if (g < 2) {
; #pragma unroll
;                         for (int r = 0; r < 8; ++r) s1[8 * g + r] = ex2(s1[8 * g + r]);
;                     }
;                     SCHEDB();
;                 }
.LBB0_295:
	v_exp_f32_e32 v3, v112
	v_exp_f32_e32 v4, v113
	v_exp_f32_e32 v5, v114
	v_exp_f32_e32 v6, v115
	v_exp_f32_e32 v7, v116
	v_exp_f32_e32 v8, v117
	v_exp_f32_e32 v9, v118
	v_exp_f32_e32 v10, v119
	v_add_u32_e32 v244, v2, v198
	ds_read_b128 v[240:243], v244 offset:32768
	ds_read_b128 v[236:239], v244 offset:36864
	ds_read_b128 v[232:235], v244 offset:40960
	ds_read_b128 v[228:231], v244 offset:45056
	v_add_u32_e32 v244, v2, v199
	ds_read_b128 v[216:219], v244 offset:32768
	ds_read_b128 v[184:187], v244 offset:36864
	v_cvt_pk_bf16_f32 v4, v3, v4
	v_cvt_pk_bf16_f32 v5, v5, v6
	v_cvt_pk_bf16_f32 v6, v7, v8
	v_cvt_pk_bf16_f32 v7, v9, v10
	s_waitcnt lgkmcnt(5)
	s_nop 0
	v_mfma_f32_32x32x16_bf16 v[16:31], v[4:7], v[240:243], v[16:31]
	ds_read_b128 v[240:243], v244 offset:40960
	s_mov_b32 s9, s8
	s_mov_b32 s10, s8
	s_mov_b32 s11, s8
	v_exp_f32_e32 v3, v120
	v_exp_f32_e32 v113, v121
	v_exp_f32_e32 v114, v122
	s_waitcnt lgkmcnt(5)
	v_mfma_f32_32x32x16_bf16 v[32:47], v[4:7], v[236:239], v[32:47]
	ds_read_b128 v[236:239], v244 offset:45056
	v_exp_f32_e32 v112, v123
	v_exp_f32_e32 v115, v124
	v_exp_f32_e32 v116, v125
	v_exp_f32_e32 v117, v126
	v_exp_f32_e32 v118, v127
	v_exp_f32_e32 v119, v96
	s_waitcnt lgkmcnt(5)
	v_mfma_f32_32x32x16_bf16 v[48:63], v[4:7], v[232:235], v[48:63]
	v_add_u32_e32 v244, v2, v200
	ds_read_b128 v[232:235], v244 offset:32768
	v_mov_b64_e32 v[8:9], s[8:9]
	v_mov_b64_e32 v[10:11], s[10:11]
	v_exp_f32_e32 v120, v97
	v_exp_f32_e32 v121, v98
	v_exp_f32_e32 v122, v99
	v_exp_f32_e32 v100, v100
	v_exp_f32_e32 v101, v101
	s_waitcnt lgkmcnt(5)
	v_mfma_f32_32x32x16_bf16 v[64:79], v[4:7], v[228:231], v[64:79]
	ds_read_b128 v[228:231], v244 offset:36864
	v_exp_f32_e32 v102, v102
	v_exp_f32_e32 v103, v103
	v_mfma_f32_32x32x16_bf16 v[80:95], v[4:7], v[8:11], v[80:95]
	v_cvt_pk_bf16_f32 v4, v3, v113
	v_cvt_pk_bf16_f32 v5, v114, v112
	v_cvt_pk_bf16_f32 v6, v115, v116
	v_cvt_pk_bf16_f32 v7, v117, v118
	s_waitcnt lgkmcnt(5)
	s_nop 0
	v_mfma_f32_32x32x16_bf16 v[16:31], v[4:7], v[216:219], v[16:31]
	ds_read_b128 v[216:219], v244 offset:40960
	v_exp_f32_e32 v3, v104
	v_exp_f32_e32 v104, v105
	v_exp_f32_e32 v105, v106
	v_exp_f32_e32 v106, v107
	v_exp_f32_e32 v107, v108
	v_exp_f32_e32 v108, v109
	v_exp_f32_e32 v109, v110
	s_waitcnt lgkmcnt(5)
	v_mfma_f32_32x32x16_bf16 v[32:47], v[4:7], v[184:187], v[32:47]
	ds_read_b128 v[184:187], v244 offset:45056
	v_exp_f32_e32 v110, v111
	s_waitcnt lgkmcnt(5)
	v_mfma_f32_32x32x16_bf16 v[48:63], v[4:7], v[240:243], v[48:63]
	v_add_u32_e32 v244, v2, v201
	ds_read_b128 v[240:243], v244 offset:32768
	s_waitcnt lgkmcnt(5)
	v_mfma_f32_32x32x16_bf16 v[64:79], v[4:7], v[236:239], v[64:79]
	ds_read_b128 v[236:239], v244 offset:36864
	v_mfma_f32_32x32x16_bf16 v[80:95], v[4:7], v[8:11], v[80:95]
	v_cvt_pk_bf16_f32 v4, v119, v120
	v_cvt_pk_bf16_f32 v5, v121, v122
	v_cvt_pk_bf16_f32 v6, v100, v101
	v_cvt_pk_bf16_f32 v7, v102, v103
	s_waitcnt lgkmcnt(5)
	s_nop 0
	v_mfma_f32_32x32x16_bf16 v[16:31], v[4:7], v[232:235], v[16:31]
	ds_read_b128 v[232:235], v244 offset:40960
	s_waitcnt lgkmcnt(5)
	v_mfma_f32_32x32x16_bf16 v[32:47], v[4:7], v[228:231], v[32:47]
	ds_read_b128 v[228:231], v244 offset:45056
	s_waitcnt lgkmcnt(5)
	v_mfma_f32_32x32x16_bf16 v[48:63], v[4:7], v[216:219], v[48:63]
	s_waitcnt lgkmcnt(4)
	v_mfma_f32_32x32x16_bf16 v[64:79], v[4:7], v[184:187], v[64:79]
	v_mfma_f32_32x32x16_bf16 v[80:95], v[4:7], v[8:11], v[80:95]
	v_cvt_pk_bf16_f32 v2, v3, v104
	v_cvt_pk_bf16_f32 v3, v105, v106
	v_cvt_pk_bf16_f32 v4, v107, v108
	v_cvt_pk_bf16_f32 v5, v109, v110
	s_waitcnt lgkmcnt(3)
	s_nop 0
	v_mfma_f32_32x32x16_bf16 v[16:31], v[2:5], v[240:243], v[16:31]
	s_waitcnt lgkmcnt(2)
	v_mfma_f32_32x32x16_bf16 v[32:47], v[2:5], v[236:239], v[32:47]
	s_waitcnt lgkmcnt(1)
	v_mfma_f32_32x32x16_bf16 v[48:63], v[2:5], v[232:235], v[48:63]
	s_waitcnt lgkmcnt(0)
	v_mfma_f32_32x32x16_bf16 v[64:79], v[2:5], v[228:231], v[64:79]
	v_mfma_f32_32x32x16_bf16 v[80:95], v[2:5], v[8:11], v[80:95]

; #define LAS __attribute__((address_space(3)))
; __device__ __forceinline__ float ex2(float v) { return __builtin_amdgcn_exp2f(v); }
; #define MFMA32(a, b, c) __builtin_amdgcn_mfma_f32_32x32x16_bf16((a), (b), (c), 0, 0, 0)
; #define SCHEDB() __builtin_amdgcn_sched_barrier(0)
; __device__ __forceinline__ void diff_unit(const Params& p, LAS unsigned char* lds, int b, int h, int qb, float lam) {
;     ...
; #pragma unroll
;                 for (int r = 0; r < 16; ++r) s0[r] = ex2(s0[r]);
; #pragma unroll
;                 for (int g = 0; g < 4; ++g) {
;                     const int co = ((4 * (g >> 1) + (g & 1)) ^ xv) << 4;
;                     bf16x8 vf[4];
; #pragma unroll
;                     for (int db = 0; db < 4; ++db) vf[db] = *(const LAS bf16x8*)(vb + db * 4096 + co);
;                     const bf16x8 pf = pack8((g >> 1) ? s1 : s0, 8 * (g & 1));
; #pragma unroll
;                     for (int db = 0; db < 4; ++db) O[db] = MFMA32(pf, vf[db], O[db]);
;                     L = MFMA32(pf, ones, L);
;                     if (g < 2) {
; #pragma unroll
;                         for (int r = 0; r < 8; ++r) s1[8 * g + r] = ex2(s1[8 * g + r]);
;                     }
;                     SCHEDB();
;                 }
.LBB0_303:
	v_add_u32_e32 v244, v0, v198
	ds_read_b128 v[240:243], v244 offset:32768
	ds_read_b128 v[236:239], v244 offset:36864
	ds_read_b128 v[232:235], v244 offset:40960
	ds_read_b128 v[228:231], v244 offset:45056
	v_add_u32_e32 v244, v0, v199
	ds_read_b128 v[184:187], v244 offset:32768
	ds_read_b128 v[176:179], v244 offset:36864
	v_exp_f32_e32 v128, v128
	v_exp_f32_e32 v129, v129
	v_exp_f32_e32 v130, v130
	v_exp_f32_e32 v131, v131
	v_exp_f32_e32 v132, v132
	v_exp_f32_e32 v133, v133
	v_exp_f32_e32 v134, v134
	v_exp_f32_e32 v135, v135
	v_cvt_pk_bf16_f32 v128, v128, v129
	v_cvt_pk_bf16_f32 v129, v130, v131
	v_cvt_pk_bf16_f32 v130, v132, v133
	v_cvt_pk_bf16_f32 v131, v134, v135
	s_waitcnt lgkmcnt(5)
	s_nop 0
	v_mfma_f32_32x32x16_bf16 v[16:31], v[128:131], v[240:243], v[16:31]
	ds_read_b128 v[240:243], v244 offset:40960
	s_mov_b32 s10, s8
	s_mov_b32 s11, s8
	s_mov_b32 s9, s8
	v_exp_f32_e32 v136, v136
	v_exp_f32_e32 v137, v137
	v_exp_f32_e32 v138, v138
	s_waitcnt lgkmcnt(5)
	v_mfma_f32_32x32x16_bf16 v[32:47], v[128:131], v[236:239], v[32:47]
	ds_read_b128 v[236:239], v244 offset:45056
	v_exp_f32_e32 v139, v139
	v_exp_f32_e32 v140, v140
	v_exp_f32_e32 v141, v141
	v_exp_f32_e32 v142, v142
	v_exp_f32_e32 v143, v143
	v_exp_f32_e32 v213, v112
	s_waitcnt lgkmcnt(5)
	v_mfma_f32_32x32x16_bf16 v[48:63], v[128:131], v[232:235], v[48:63]
	v_add_u32_e32 v244, v0, v200
	ds_read_b128 v[232:235], v244 offset:32768
	v_mov_b64_e32 v[134:135], s[10:11]
	v_mov_b64_e32 v[132:133], s[8:9]
	v_exp_f32_e32 v218, v117
	v_exp_f32_e32 v219, v118
	v_exp_f32_e32 v220, v119
	s_waitcnt lgkmcnt(5)
	v_mfma_f32_32x32x16_bf16 v[64:79], v[128:131], v[228:231], v[64:79]
	ds_read_b128 v[228:231], v244 offset:36864
	v_exp_f32_e32 v214, v113
	v_exp_f32_e32 v215, v114
	v_exp_f32_e32 v216, v115
	v_exp_f32_e32 v217, v116
	v_mfma_f32_32x32x16_bf16 v[80:95], v[128:131], v[132:135], v[80:95]
	v_cvt_pk_bf16_f32 v112, v136, v137
	v_cvt_pk_bf16_f32 v113, v138, v139
	v_cvt_pk_bf16_f32 v114, v140, v141
	v_cvt_pk_bf16_f32 v115, v142, v143
	s_waitcnt lgkmcnt(5)
	s_nop 0
	v_mfma_f32_32x32x16_bf16 v[16:31], v[112:115], v[184:187], v[16:31]
	ds_read_b128 v[184:187], v244 offset:40960
	v_exp_f32_e32 v124, v124
	v_exp_f32_e32 v125, v125
	v_exp_f32_e32 v126, v126
	v_exp_f32_e32 v127, v127
	s_waitcnt lgkmcnt(5)
	v_mfma_f32_32x32x16_bf16 v[32:47], v[112:115], v[176:179], v[32:47]
	ds_read_b128 v[176:179], v244 offset:45056
	s_waitcnt lgkmcnt(5)
	v_mfma_f32_32x32x16_bf16 v[48:63], v[112:115], v[240:243], v[48:63]
	v_add_u32_e32 v244, v0, v201
	ds_read_b128 v[240:243], v244 offset:32768
	s_waitcnt lgkmcnt(5)
	v_mfma_f32_32x32x16_bf16 v[64:79], v[112:115], v[236:239], v[64:79]
	ds_read_b128 v[236:239], v244 offset:36864
	v_exp_f32_e32 v128, v120
	v_exp_f32_e32 v129, v121
	v_exp_f32_e32 v130, v122
	v_exp_f32_e32 v131, v123
	v_mfma_f32_32x32x16_bf16 v[80:95], v[112:115], v[132:135], v[80:95]
	v_cvt_pk_bf16_f32 v112, v213, v214
	v_cvt_pk_bf16_f32 v113, v215, v216
	v_cvt_pk_bf16_f32 v114, v217, v218
	v_cvt_pk_bf16_f32 v115, v219, v220
	s_waitcnt lgkmcnt(5)
	s_nop 0
	v_mfma_f32_32x32x16_bf16 v[16:31], v[112:115], v[232:235], v[16:31]
	ds_read_b128 v[232:235], v244 offset:40960
	s_waitcnt lgkmcnt(5)
	v_mfma_f32_32x32x16_bf16 v[32:47], v[112:115], v[228:231], v[32:47]
	ds_read_b128 v[228:231], v244 offset:45056
	s_waitcnt lgkmcnt(5)
	v_mfma_f32_32x32x16_bf16 v[48:63], v[112:115], v[184:187], v[48:63]
	s_waitcnt lgkmcnt(4)
	v_mfma_f32_32x32x16_bf16 v[64:79], v[112:115], v[176:179], v[64:79]
	v_mfma_f32_32x32x16_bf16 v[80:95], v[112:115], v[132:135], v[80:95]
	v_add_u32_e32 v0, v0, v201
	v_cvt_pk_bf16_f32 v112, v128, v129
	v_cvt_pk_bf16_f32 v113, v130, v131
	v_cvt_pk_bf16_f32 v114, v124, v125
	v_cvt_pk_bf16_f32 v115, v126, v127
	s_waitcnt lgkmcnt(3)
	s_nop 0
	v_mfma_f32_32x32x16_bf16 v[16:31], v[112:115], v[240:243], v[16:31]
	s_waitcnt lgkmcnt(2)
	v_mfma_f32_32x32x16_bf16 v[32:47], v[112:115], v[236:239], v[32:47]
	s_waitcnt lgkmcnt(1)
	v_mfma_f32_32x32x16_bf16 v[48:63], v[112:115], v[232:235], v[48:63]
	s_waitcnt lgkmcnt(0)
	v_mfma_f32_32x32x16_bf16 v[64:79], v[112:115], v[228:231], v[64:79]
	v_mfma_f32_32x32x16_bf16 v[80:95], v[112:115], v[132:135], v[80:95]

; #define LAS __attribute__((address_space(3)))
; #define MFMA32(a, b, c) __builtin_amdgcn_mfma_f32_32x32x16_bf16((a), (b), (c), 0, 0, 0)
; #define SCHEDB() __builtin_amdgcn_sched_barrier(0)
; __device__ __forceinline__ void diff_unit(const Params& p, LAS unsigned char* lds, int b, int h, int qb, float lam) {
;     ...
;         for (int jt = 0; jt < NT; ++jt) {
;             const int cur = jt & 1;
;             if (jt + 1 < NT) tile_dma<64>(Kg0 + (size_t)(jt + 1) * 4096, Vg0 + (size_t)(jt + 1) * 8192, lds + A_KOFF + (cur ^ 1) * A_KBUF, lds + A_VOFF + (cur ^ 1) * A_VBUF, wid, lane);
;             if (jt <= mylast) {
;                 const LAS unsigned char* kb = lds + A_KOFF + cur * A_KBUF + c * 128;
;                 const LAS unsigned char* vb = lds + A_VOFF + cur * A_VBUF + c * 128;
;                 f32x16 s0, s1;
;                 {
;                     bf16x8 a[2][2];
;                     { const int co = (0 ^ xk) << 4; a[0][0] = *(const LAS bf16x8*)(kb + co); a[0][1] = *(const LAS bf16x8*)(kb + 4096 + co); }
; #pragma unroll
;                     for (int ks = 0; ks < 4; ++ks) {
;                         if (ks + 1 < 4) { const int co = ((2 * (ks + 1)) ^ xk) << 4; a[(ks + 1) & 1][0] = *(const LAS bf16x8*)(kb + co); a[(ks + 1) & 1][1] = *(const LAS bf16x8*)(kb + 4096 + co); }
;                         if (ks == 0) { s0 = MFMA32(a[0][0], qf[0], negm); s1 = MFMA32(a[0][1], qf[0], negm); }
;                         else { s0 = MFMA32(a[ks & 1][0], qf[ks], s0); s1 = MFMA32(a[ks & 1][1], qf[ks], s1); }
;                         SCHEDB();
;                     }
;                 }
;                 if ((q0 - (64 * jt + 63)) < 91) {
;                     const int idx0 = (q0 + c) - (64 * jt + 16 * hh) + 64;
; #pragma unroll
;                     for (int r = 0; r < 16; ++r) { s0[r] += tab[min(idx0 - r, 255)]; s1[r] += tab[min(idx0 - 32 - r, 255)]; if ((r & 3) == 3) SCHEDB(); }
;                 }
.LBB0_305:
	s_mov_b64 s[10:11], s[64:65]
	s_add_u32 s64, s10, 0x4000
	s_addc_u32 s65, s11, 0
	s_and_b32 s1, s64, 0x4000
	s_xor_b32 s3, s1, 0x4000
	s_add_i32 s6, s3, 0
	s_cmp_gt_i32 s0, s76
	s_cbranch_scc1 .Lqs1_dma_only
	v_add_u32_e32 v0, s1, v197
	v_add_u32_e32 v213, v0, v203
	ds_read_b128 v[214:217], v213
	ds_read_b128 v[218:221], v213 offset:4096
	v_add_u32_e32 v213, v0, v205
	ds_read_b128 v[222:225], v213
	ds_read_b128 v[2:5], v213 offset:4096
	v_add_u32_e32 v213, v0, v206
	ds_read_b128 v[6:9], v213
	ds_read_b128 v[10:13], v213 offset:4096
	v_add_u32_e32 v213, v0, v207
	ds_read_b128 v[228:231], v213
	ds_read_b128 v[232:235], v213 offset:4096
	s_add_i32 m0, s78, s3
	s_add_i32 s3, s6, s80
	global_load_lds_dwordx4 v[180:181], off
	v_lshl_add_u64 v[112:113], v[166:167], 0, s[10:11]
	s_add_i32 m0, s3, 0x8000
	s_add_i32 s3, s6, s79
	global_load_lds_dwordx4 v[112:113], off
	v_lshl_add_u64 v[112:113], v[168:169], 0, s[10:11]
	s_add_i32 m0, s3, 0x8000
	s_nop 0
	global_load_lds_dwordx4 v[112:113], off
	s_waitcnt lgkmcnt(7)
	v_mfma_f32_32x32x16_bf16 v[128:143], v[214:217], v[156:159], v[96:111]
	s_waitcnt lgkmcnt(6)
	v_mfma_f32_32x32x16_bf16 v[112:127], v[218:221], v[156:159], v[96:111]
	s_waitcnt lgkmcnt(5)
	v_mfma_f32_32x32x16_bf16 v[128:143], v[222:225], v[152:155], v[128:143]
	s_waitcnt lgkmcnt(4)
	v_mfma_f32_32x32x16_bf16 v[112:127], v[2:5], v[152:155], v[112:127]
	s_waitcnt lgkmcnt(3)
	v_mfma_f32_32x32x16_bf16 v[128:143], v[6:9], v[148:151], v[128:143]
	s_waitcnt lgkmcnt(2)
	v_mfma_f32_32x32x16_bf16 v[112:127], v[10:13], v[148:151], v[112:127]
	s_waitcnt lgkmcnt(1)
	v_mfma_f32_32x32x16_bf16 v[128:143], v[228:231], v[144:147], v[128:143]
	s_waitcnt lgkmcnt(0)
	v_mfma_f32_32x32x16_bf16 v[112:127], v[232:235], v[144:147], v[112:127]
	s_add_i32 s1, s77, 0xffffff81
	s_cmpk_gt_i32 s1, 0x5a
	s_cbranch_scc1 .LBB0_308
	v_add_u32_e32 v213, s77, v208
	s_add_i32 s1, 0, 0x10000
	v_min_i32_e32 v216, 0xc0, v213
	v_lshl_add_u32 v217, v216, 2, s1
	v_min_i32_e32 v216, 0xe0, v213
	v_lshl_add_u32 v218, v216, 2, s1
	v_min_i32_e32 v216, 0xc1, v213
	v_lshl_add_u32 v219, v216, 2, s1
	v_min_i32_e32 v216, 0xe1, v213
	v_min_i32_e32 v214, 0xbf, v213
	v_min_i32_e32 v215, 0xdf, v213
	v_lshl_add_u32 v220, v216, 2, s1
	v_min_i32_e32 v216, 0xc2, v213
	v_lshl_add_u32 v214, v214, 2, s1
	v_lshl_add_u32 v215, v215, 2, s1
	v_lshl_add_u32 v221, v216, 2, s1
	v_min_i32_e32 v216, 0xe2, v213
	v_lshl_add_u32 v222, v216, 2, s1
	ds_read_b32 v214, v214 offset:256
	ds_read_b32 v216, v215 offset:128
	ds_read_b32 v215, v217 offset:252
	ds_read_b32 v217, v218 offset:124
	ds_read_b32 v218, v219 offset:248
	ds_read_b32 v220, v220 offset:120
	ds_read_b32 v219, v221 offset:244
	ds_read_b32 v221, v222 offset:116
	v_min_i32_e32 v224, 0xc4, v213
	v_lshl_add_u32 v225, v224, 2, s1
	v_min_i32_e32 v224, 0xe4, v213
	v_lshl_add_u32 v226, v224, 2, s1
	v_min_i32_e32 v224, 0xc5, v213
	v_lshl_add_u32 v227, v224, 2, s1
	v_min_i32_e32 v224, 0xe5, v213
	v_min_i32_e32 v222, 0xc3, v213
	v_min_i32_e32 v223, 0xe3, v213
	v_lshl_add_u32 v228, v224, 2, s1
	v_min_i32_e32 v224, 0xc6, v213
	v_lshl_add_u32 v222, v222, 2, s1
	v_lshl_add_u32 v223, v223, 2, s1
	v_lshl_add_u32 v229, v224, 2, s1
	v_min_i32_e32 v224, 0xe6, v213
	v_lshl_add_u32 v230, v224, 2, s1
	ds_read_b32 v222, v222 offset:240
	ds_read_b32 v224, v223 offset:112
	ds_read_b32 v223, v225 offset:236
	ds_read_b32 v225, v226 offset:108
	ds_read_b32 v226, v227 offset:232
	ds_read_b32 v228, v228 offset:104
	ds_read_b32 v227, v229 offset:228
	ds_read_b32 v229, v230 offset:100
	v_min_i32_e32 v232, 0xc8, v213
	v_lshl_add_u32 v233, v232, 2, s1
	v_min_i32_e32 v232, 0xe8, v213
	v_lshl_add_u32 v234, v232, 2, s1
	v_min_i32_e32 v232, 0xc9, v213
	v_lshl_add_u32 v235, v232, 2, s1
	v_min_i32_e32 v232, 0xe9, v213
	v_min_i32_e32 v230, 0xc7, v213
	v_min_i32_e32 v231, 0xe7, v213
	v_lshl_add_u32 v236, v232, 2, s1
	v_min_i32_e32 v232, 0xca, v213
	v_lshl_add_u32 v230, v230, 2, s1
	v_lshl_add_u32 v231, v231, 2, s1
	v_lshl_add_u32 v237, v232, 2, s1
	v_min_i32_e32 v232, 0xea, v213
	v_lshl_add_u32 v238, v232, 2, s1
	ds_read_b32 v230, v230 offset:224
	ds_read_b32 v232, v231 offset:96
	ds_read_b32 v231, v233 offset:220
	ds_read_b32 v233, v234 offset:92
	ds_read_b32 v234, v235 offset:216
	ds_read_b32 v236, v236 offset:88
	ds_read_b32 v235, v237 offset:212
	ds_read_b32 v237, v238 offset:84
	v_min_i32_e32 v238, 0xcb, v213
	v_lshl_add_u32 v238, v238, 2, s1
	v_min_i32_e32 v239, 0xeb, v213
	v_min_i32_e32 v240, 0xcc, v213
	v_min_i32_e32 v241, 0xec, v213
	v_min_i32_e32 v242, 0xcd, v213
	v_min_i32_e32 v243, 0xed, v213
	v_min_i32_e32 v244, 0xce, v213
	v_min_i32_e32 v213, 0xee, v213
	v_lshl_add_u32 v239, v239, 2, s1
	v_lshl_add_u32 v240, v240, 2, s1
	v_lshl_add_u32 v241, v241, 2, s1
	v_lshl_add_u32 v242, v242, 2, s1
	v_lshl_add_u32 v243, v243, 2, s1
	v_lshl_add_u32 v244, v244, 2, s1
	s_waitcnt lgkmcnt(0)
	v_pk_add_f32 v[130:131], v[130:131], v[218:219]
	v_pk_add_f32 v[128:129], v[128:129], v[214:215]
	v_pk_add_f32 v[134:135], v[134:135], v[226:227]
	v_pk_add_f32 v[132:133], v[132:133], v[222:223]
	v_lshl_add_u32 v213, v213, 2, s1
	ds_read_b32 v214, v238 offset:208
	ds_read_b32 v218, v239 offset:80
	ds_read_b32 v222, v242 offset:200
	ds_read_b32 v223, v244 offset:196
	ds_read_b32 v215, v240 offset:204
	ds_read_b32 v227, v213 offset:68
	ds_read_b32 v226, v243 offset:72
	ds_read_b32 v219, v241 offset:76
	v_pk_add_f32 v[138:139], v[138:139], v[234:235]
	v_pk_add_f32 v[136:137], v[136:137], v[230:231]
	s_waitcnt lgkmcnt(0)
	v_pk_add_f32 v[142:143], v[142:143], v[222:223]
	v_pk_add_f32 v[140:141], v[140:141], v[214:215]
	v_pk_add_f32 v[114:115], v[114:115], v[220:221]
	v_pk_add_f32 v[112:113], v[112:113], v[216:217]
	v_pk_add_f32 v[118:119], v[118:119], v[228:229]
	v_pk_add_f32 v[116:117], v[116:117], v[224:225]
	v_pk_add_f32 v[122:123], v[122:123], v[236:237]
	v_pk_add_f32 v[120:121], v[120:121], v[232:233]
	v_pk_add_f32 v[126:127], v[126:127], v[226:227]
	v_pk_add_f32 v[124:125], v[124:125], v[218:219]

; __device__ __forceinline__ void diff_unit(const Params& p, LAS unsigned char* lds, int b, int h, int qb, float lam) {
;     ...
;             if (jt + 1 < NT) tile_dma<64>(Kg0 + (size_t)(jt + 1) * 4096, Vg0 + (size_t)(jt + 1) * 8192, lds + A_KOFF + (cur ^ 1) * A_KBUF, lds + A_VOFF + (cur ^ 1) * A_VBUF, wid, lane);
;             if (jt <= mylast) {
.Lqs1_dma_only:
	s_add_i32 m0, s78, s3
	s_add_i32 s3, s6, s80
	global_load_lds_dwordx4 v[180:181], off
	v_lshl_add_u64 v[112:113], v[166:167], 0, s[10:11]
	s_add_i32 m0, s3, 0x8000
	s_add_i32 s3, s6, s79
	global_load_lds_dwordx4 v[112:113], off
	v_lshl_add_u64 v[112:113], v[168:169], 0, s[10:11]
	s_add_i32 m0, s3, 0x8000
	s_nop 0
	global_load_lds_dwordx4 v[112:113], off
	s_branch .LBB0_304
